# remaining two weight-conversion loops: batched LDS reads
# baseline (speedup 1.0000x reference)
.LBB0_25:
	s_ashr_i32 s17, s1, 31
	s_lshr_b32 s17, s17, 25
	s_add_i32 s17, s1, s17
	s_ashr_i32 s17, s17, 7
	s_lshl_b32 s19, s17, 12
	s_lshl_b32 s18, s17, 6
	s_sub_i32 s20, s4, s19
	v_add_u32_e32 v24, s18, v6
	s_ashr_i32 s21, s20, 31
	v_ashrrev_i32_e32 v25, 31, v24
	v_lshl_add_u64 v[26:27], s[20:21], 2, v[2:3]
	v_lshlrev_b64 v[24:25], 14, v[24:25]
	v_lshl_add_u64 v[28:29], v[26:27], 0, v[24:25]
	v_add_co_u32_e32 v56, vcc, s10, v28
	global_load_dwordx4 v[24:27], v[28:29], off
	s_nop 0
	v_addc_co_u32_e32 v57, vcc, 0, v29, vcc
	v_add_co_u32_e32 v58, vcc, s11, v28
	s_lshl_b32 s17, s17, 8
	s_nop 0
	v_addc_co_u32_e32 v59, vcc, 0, v29, vcc
	v_add_co_u32_e32 v60, vcc, s12, v28
	s_sub_i32 s21, s6, s19
	s_nop 0
	v_addc_co_u32_e32 v61, vcc, 0, v29, vcc
	v_add_co_u32_e32 v62, vcc, s13, v28
	s_sub_i32 s17, s8, s17
	s_nop 0
	v_addc_co_u32_e32 v63, vcc, 0, v29, vcc
	v_add_co_u32_e32 v64, vcc, s14, v28
	s_and_b32 s21, s21, 0xf00
	s_nop 0
	v_addc_co_u32_e32 v65, vcc, 0, v29, vcc
	v_add_co_u32_e32 v66, vcc, s15, v28
	s_and_b32 s17, s17, 0xffffff80
	s_nop 0
	v_addc_co_u32_e32 v67, vcc, 0, v29, vcc
	v_add_co_u32_e32 v68, vcc, s16, v28
	s_and_b32 s20, s20, 0x60
	s_nop 0
	v_addc_co_u32_e32 v69, vcc, 0, v29, vcc
	global_load_dwordx4 v[28:31], v[56:57], off
	global_load_dwordx4 v[32:35], v[58:59], off
	global_load_dwordx4 v[36:39], v[60:61], off
	global_load_dwordx4 v[40:43], v[62:63], off
	global_load_dwordx4 v[44:47], v[64:65], off
	global_load_dwordx4 v[48:51], v[66:67], off
	global_load_dwordx4 v[52:55], v[68:69], off
	s_add_i32 s21, s21, s17
	s_or_b32 s17, s21, s20
	v_add_u32_e32 v58, s17, v6
	s_ashr_i32 s19, s18, 31
	v_ashrrev_i32_e32 v59, 31, v58
	v_lshl_add_u64 v[56:57], s[18:19], 1, v[4:5]
	v_lshlrev_b64 v[64:65], 12, v[58:59]
	v_lshl_add_u64 v[64:65], v[56:57], 0, v[64:65]
	v_add_u32_e32 v60, 8, v58
	v_ashrrev_i32_e32 v61, 31, v60
	v_lshlrev_b64 v[60:61], 12, v[60:61]
	v_lshl_add_u64 v[60:61], v[56:57], 0, v[60:61]
	v_add_u32_e32 v62, 16, v58
	v_ashrrev_i32_e32 v63, 31, v62
	v_lshlrev_b64 v[62:63], 12, v[62:63]
	s_add_i32 s1, s1, s68
	s_add_i32 s4, s4, s5
	s_add_i32 s6, s6, s7
	s_add_i32 s8, s8, s9
	s_cmpk_lt_i32 s1, 0x1000
	s_waitcnt vmcnt(0) lgkmcnt(0)
	ds_write2_b32 v8, v24, v25 offset1:1
	ds_write2_b32 v8, v26, v27 offset0:2 offset1:3
	ds_write2_b32 v9, v28, v29 offset1:1
	ds_write2_b32 v10, v30, v31 offset1:1
	ds_write2_b32 v11, v32, v33 offset1:1
	ds_write2_b32 v12, v34, v35 offset1:1
	ds_write2_b32 v13, v36, v37 offset1:1
	ds_write2_b32 v14, v38, v39 offset1:1
	ds_write2_b32 v15, v40, v41 offset1:1
	ds_write2_b32 v16, v42, v43 offset1:1
	ds_write2_b32 v17, v44, v45 offset1:1
	ds_write2_b32 v18, v46, v47 offset1:1
	ds_write2_b32 v19, v48, v49 offset1:1
	ds_write2_b32 v20, v50, v51 offset1:1
	ds_write2_b32 v21, v52, v53 offset1:1
	ds_write2_b32 v22, v54, v55 offset1:1
	s_waitcnt lgkmcnt(0)
	ds_read2_b32 v[102:103], v7 offset1:33
	ds_read2_b32 v[104:105], v7 offset0:66 offset1:99
	ds_read2_b32 v[106:107], v7 offset0:132 offset1:165
	ds_read2_b32 v[108:109], v7 offset0:198 offset1:231
	ds_read2_b32 v[110:111], v7 offset0:8 offset1:41
	ds_read2_b32 v[112:113], v7 offset0:74 offset1:107
	ds_read2_b32 v[114:115], v7 offset0:140 offset1:173
	ds_read2_b32 v[116:117], v7 offset0:206 offset1:239
	ds_read2_b32 v[118:119], v7 offset0:16 offset1:49
	ds_read2_b32 v[120:121], v7 offset0:82 offset1:115
	ds_read2_b32 v[122:123], v7 offset0:148 offset1:181
	ds_read2_b32 v[124:125], v7 offset0:214 offset1:247
	ds_read2_b32 v[126:127], v7 offset0:24 offset1:57
	ds_read2_b32 v[128:129], v7 offset0:90 offset1:123
	ds_read2_b32 v[130:131], v7 offset0:156 offset1:189
	ds_read2_b32 v[132:133], v7 offset0:222 offset1:255
	s_waitcnt lgkmcnt(0)
	v_cvt_pk_bf16_f32 v24, v102, v103
	v_cvt_pk_bf16_f32 v25, v104, v105
	v_cvt_pk_bf16_f32 v26, v106, v107
	v_cvt_pk_bf16_f32 v27, v108, v109
	global_store_dwordx4 v[64:65], v[24:27], off
	s_nop 1
	v_lshl_add_u64 v[30:31], v[56:57], 0, v[62:63]
	v_cvt_pk_bf16_f32 v24, v110, v111
	v_cvt_pk_bf16_f32 v25, v112, v113
	v_cvt_pk_bf16_f32 v26, v114, v115
	v_cvt_pk_bf16_f32 v27, v116, v117
	global_store_dwordx4 v[60:61], v[24:27], off
	s_nop 1
	v_cvt_pk_bf16_f32 v24, v118, v119
	v_cvt_pk_bf16_f32 v25, v120, v121
	v_cvt_pk_bf16_f32 v26, v122, v123
	v_cvt_pk_bf16_f32 v27, v124, v125
	global_store_dwordx4 v[30:31], v[24:27], off
	s_nop 1
	v_add_u32_e32 v30, 24, v58
	v_ashrrev_i32_e32 v31, 31, v30
	v_cvt_pk_bf16_f32 v24, v126, v127
	v_lshlrev_b64 v[30:31], 12, v[30:31]
	v_cvt_pk_bf16_f32 v25, v128, v129
	v_lshl_add_u64 v[30:31], v[56:57], 0, v[30:31]
	v_cvt_pk_bf16_f32 v26, v130, v131
	v_cvt_pk_bf16_f32 v27, v132, v133
	global_store_dwordx4 v[30:31], v[24:27], off
	s_waitcnt lgkmcnt(0)
	s_cbranch_scc1 .LBB0_25

.LBB0_28:
	s_or_b64 exec, exec, s[6:7]
	s_waitcnt vmcnt(0) lgkmcnt(0)
	ds_write2_b32 v45, v2, v3 offset1:1
	ds_write2_b32 v45, v4, v5 offset0:2 offset1:3
	v_add_u32_e32 v2, 0x420, v45
	ds_write2_b32 v2, v10, v11 offset1:1
	v_add_u32_e32 v2, 0x428, v45
	ds_write2_b32 v2, v12, v13 offset1:1
	v_add_u32_e32 v2, 0x840, v45
	ds_write2_b32 v2, v6, v7 offset1:1
	v_add_u32_e32 v2, 0x848, v45
	ds_write2_b32 v2, v8, v9 offset1:1
	v_add_u32_e32 v2, 0xc60, v45
	ds_write2_b32 v2, v18, v19 offset1:1
	v_add_u32_e32 v2, 0xc68, v45
	ds_write2_b32 v2, v20, v21 offset1:1
	v_add_u32_e32 v2, 0x1080, v45
	ds_write2_b32 v2, v14, v15 offset1:1
	v_add_u32_e32 v2, 0x1088, v45
	ds_write2_b32 v2, v16, v17 offset1:1
	v_add_u32_e32 v2, 0x14a0, v45
	ds_write2_b32 v2, v26, v27 offset1:1
	v_add_u32_e32 v2, 0x14a8, v45
	ds_write2_b32 v2, v28, v29 offset1:1
	v_add_u32_e32 v2, 0x18c0, v45
	ds_write2_b32 v2, v22, v23 offset1:1
	v_add_u32_e32 v2, 0x18c8, v45
	ds_write2_b32 v2, v24, v25 offset1:1
	v_add_u32_e32 v2, 0x1ce0, v45
	ds_write2_b32 v2, v30, v31 offset1:1
	v_add_u32_e32 v2, 0x1ce8, v45
	ds_write2_b32 v2, v32, v33 offset1:1
	s_waitcnt lgkmcnt(0)
	ds_read2_b32 v[102:103], v44 offset1:33
	ds_read2_b32 v[104:105], v44 offset0:66 offset1:99
	ds_read2_b32 v[106:107], v44 offset0:132 offset1:165
	ds_read2_b32 v[108:109], v44 offset0:198 offset1:231
	ds_read2_b32 v[110:111], v44 offset0:8 offset1:41
	ds_read2_b32 v[112:113], v44 offset0:74 offset1:107
	ds_read2_b32 v[114:115], v44 offset0:140 offset1:173
	ds_read2_b32 v[116:117], v44 offset0:206 offset1:239
	ds_read2_b32 v[118:119], v44 offset0:16 offset1:49
	ds_read2_b32 v[120:121], v44 offset0:82 offset1:115
	ds_read2_b32 v[122:123], v44 offset0:148 offset1:181
	ds_read2_b32 v[124:125], v44 offset0:214 offset1:247
	ds_read2_b32 v[126:127], v44 offset0:24 offset1:57
	ds_read2_b32 v[128:129], v44 offset0:90 offset1:123
	ds_read2_b32 v[130:131], v44 offset0:156 offset1:189
	ds_read2_b32 v[132:133], v44 offset0:222 offset1:255
	s_waitcnt lgkmcnt(0)
	v_cvt_pk_bf16_f32 v2, v102, v103
	v_cvt_pk_bf16_f32 v3, v104, v105
	s_sub_i32 s6, 0, s5
	v_cvt_pk_bf16_f32 v4, v106, v107
	s_add_i32 s6, s6, s8
	v_cvt_pk_bf16_f32 v5, v108, v109
	v_add_u32_e32 v6, s6, v42
	s_ashr_i32 s5, s4, 31
	v_ashrrev_i32_e32 v7, 31, v6
	v_lshl_add_u64 v[8:9], s[4:5], 1, v[36:37]
	v_lshlrev_b64 v[10:11], 12, v[6:7]
	v_lshl_add_u64 v[10:11], v[8:9], 0, v[10:11]
	global_store_dwordx4 v[10:11], v[2:5], off
	s_nop 1
	s_add_i32 s1, s1, s68
	v_cvt_pk_bf16_f32 v2, v110, v111
	v_cvt_pk_bf16_f32 v3, v112, v113
	v_cvt_pk_bf16_f32 v4, v114, v115
	v_cvt_pk_bf16_f32 v5, v116, v117
	v_add_u32_e32 v10, 8, v6
	v_ashrrev_i32_e32 v11, 31, v10
	v_lshlrev_b64 v[10:11], 12, v[10:11]
	v_lshl_add_u64 v[10:11], v[8:9], 0, v[10:11]
	global_store_dwordx4 v[10:11], v[2:5], off
	s_nop 1
	s_add_i32 s8, s8, s9
	v_cvt_pk_bf16_f32 v2, v118, v119
	v_cvt_pk_bf16_f32 v3, v120, v121
	v_cvt_pk_bf16_f32 v4, v122, v123
	v_cvt_pk_bf16_f32 v5, v124, v125
	v_add_u32_e32 v10, 16, v6
	v_ashrrev_i32_e32 v11, 31, v10
	v_lshlrev_b64 v[10:11], 12, v[10:11]
	v_lshl_add_u64 v[10:11], v[8:9], 0, v[10:11]
	global_store_dwordx4 v[10:11], v[2:5], off
	s_nop 1
	v_add_u32_e32 v6, 24, v6
	v_ashrrev_i32_e32 v7, 31, v6
	v_cvt_pk_bf16_f32 v2, v126, v127
	v_lshlrev_b64 v[6:7], 12, v[6:7]
	v_cvt_pk_bf16_f32 v3, v128, v129
	v_lshl_add_u64 v[6:7], v[8:9], 0, v[6:7]
	v_cvt_pk_bf16_f32 v4, v130, v131
	v_cvt_pk_bf16_f32 v5, v132, v133
	global_store_dwordx4 v[6:7], v[2:5], off
	s_waitcnt lgkmcnt(0)
	s_cmpk_lt_i32 s1, 0x800
	s_cbranch_scc0 .LBB0_45
